# v30 + input-projection tile columns permuted so every workgroup gets 4 sigmoid-gate tiles and 3 other tiles (was 7 vs 1)
# baseline (speedup 1.0000x reference)
;     DI bool next(int i, Unit& u) const { if (!so.next(i, u)) return false; u.ak = (u.pn >= 4) ? 256 : 0; return true; }
;     DI bool next(int i, Unit& u) const { if (!so.next(i >> 2, u)) return false; u.sub = i & 3; u.ak = u.sub * 512; u.brow = u.sub * D + u.pn * BM; return true; }
;     DI bool next(int i, Unit& u) const {
;         const long L = (long)i * G + c; if (L >= nwg) return false;
;         int wgid = (int)L; { const int q = nwg / NXCD, r = nwg % NXCD, xcd = wgid % NXCD, off = wgid / NXCD; wgid = (xcd < r ? xcd * (q + 1) : r * (q + 1) + (xcd - r) * q) + off; }
;         const int nig = WGM * nN, gid = wgid / nig, fm = gid * WGM, gsz = (nM - fm) < WGM ? (nM - fm) : WGM;
;         u.pm = fm + ((wgid % nig) % gsz); u.pn = (wgid % nig) / gsz; u.ak = 0; u.brow = u.pn * BM; u.sub = 0; return true;
.LBB0_471:
	s_cmpk_lt_i32 s8, 0x700
	v_readfirstlane_b32 s26, v10
	s_cselect_b64 s[16:17], -1, 0
	s_cmpk_gt_i32 s8, 0x6ff
	s_mov_b64 s[12:13], 0
	s_waitcnt lgkmcnt(0)
	s_barrier
	s_cbranch_scc1 .LBB0_473
	s_ashr_i32 s11, s8, 31
	s_lshr_b32 s11, s11, 29
	s_add_i32 s11, s8, s11
	s_ashr_i32 s12, s11, 3
	s_and_b32 s11, s11, -8
	s_sub_i32 s11, s8, s11
	s_cmp_lt_i32 s11, 0
	s_movk_i32 s13, 0xe1
	s_cselect_b32 s13, s13, 0xe0
	s_mul_i32 s11, s11, s13
	s_add_i32 s11, s11, s12
	s_mul_hi_i32 s12, s11, 0x92492493
	s_add_i32 s12, s12, s11
	s_lshr_b32 s13, s12, 31
	s_ashr_i32 s12, s12, 8
	s_add_i32 s12, s12, s13
	s_lshl_b32 s13, s12, 3
	s_mulk_i32 s12, 0x1c0
	s_sub_i32 s11, s11, s12
	s_bfe_u32 s12, s11, 0x3001c
	s_add_i32 s12, s11, s12
	s_sext_i32_i16 s19, s12
	s_and_b32 s12, s12, 0xfff8
	s_sub_i32 s11, s11, s12
	s_ashr_i32 s52, s19, 3
	s_sext_i32_i16 s11, s11
	s_cmp_ge_u32 s52, 28
	s_cselect_b32 s12, 4, 0
	s_cselect_b32 s19, 28, 0
	s_sub_i32 s19, s52, s19
	s_lshr_b32 vcc_lo, s19, 2
	s_and_b32 s19, s19, 3
	s_add_i32 s12, s12, s19
	s_mul_i32 s19, s12, 3
	s_add_i32 s19, s19, vcc_lo
	s_lshl_b32 s12, s12, 2
	s_add_i32 s12, s12, vcc_lo
	s_add_i32 s12, s12, 21
	s_cmp_lt_u32 vcc_lo, 3
	s_cselect_b32 s52, s19, s12
	s_lshl_b32 s12, s52, 8
	s_add_i32 s18, s13, s11
	s_ashr_i32 s13, s12, 31
	s_lshl_b64 s[12:13], s[12:13], 12

;     DI bool next(int i, Unit& u) const { if (!so.next(i, u)) return false; u.ak = (u.pn >= 4) ? 256 : 0; return true; }
;     DI bool next(int i, Unit& u) const { if (!so.next(i >> 2, u)) return false; u.sub = i & 3; u.ak = u.sub * 512; u.brow = u.sub * D + u.pn * BM; return true; }
;     DI bool next(int i, Unit& u) const {
;         const long L = (long)i * G + c; if (L >= nwg) return false;
;         int wgid = (int)L; { const int q = nwg / NXCD, r = nwg % NXCD, xcd = wgid % NXCD, off = wgid / NXCD; wgid = (xcd < r ? xcd * (q + 1) : r * (q + 1) + (xcd - r) * q) + off; }
;         const int nig = WGM * nN, gid = wgid / nig, fm = gid * WGM, gsz = (nM - fm) < WGM ? (nM - fm) : WGM;
;         u.pm = fm + ((wgid % nig) % gsz); u.pn = (wgid % nig) / gsz; u.ak = 0; u.brow = u.pn * BM; u.sub = 0; return true;
.LBB0_479:
	s_add_i32 s24, s19, 1
	s_mul_i32 s30, s24, s29
	s_mul_hi_u32 s31, s24, s28
	s_add_i32 s31, s31, s30
	s_mul_i32 s30, s24, s28
	s_add_u32 s30, s30, s8
	s_addc_u32 s31, s31, s9
	v_mov_b64_e32 v[2:3], 0x700
	v_cmp_gt_i64_e32 vcc, s[30:31], v[196:197]
	v_cmp_lt_i64_e64 s[38:39], s[30:31], v[2:3]
	s_cbranch_vccnz .LBB0_481
	s_ashr_i32 s25, s30, 31
	s_lshr_b32 s25, s25, 29
	s_add_i32 s25, s30, s25
	s_ashr_i32 s31, s25, 3
	s_and_b32 s25, s25, -8
	s_sub_i32 s25, s30, s25
	s_cmp_lt_i32 s25, 0
	s_movk_i32 s30, 0xe1
	s_cselect_b32 s30, s30, 0xe0
	s_mul_i32 s25, s25, s30
	s_add_i32 s25, s25, s31
	s_mul_hi_i32 s30, s25, 0x92492493
	s_add_i32 s30, s30, s25
	s_lshr_b32 s31, s30, 31
	s_ashr_i32 s30, s30, 8
	s_add_i32 s30, s30, s31
	s_lshl_b32 s31, s30, 3
	s_sub_i32 s40, 32, s31
	s_min_i32 s40, s40, 8
	s_abs_i32 s41, s40
	v_cvt_f32_u32_e32 v2, s41
	s_sub_i32 s43, 0, s41
	s_mulk_i32 s30, 0x1c0
	s_sub_i32 s30, s25, s30
	v_rcp_iflag_f32_e32 v2, v2
	s_abs_i32 s25, s30
	s_xor_b32 s42, s30, s40
	s_ashr_i32 s42, s42, 31
	v_mul_f32_e32 v2, 0x4f7ffffe, v2
	v_cvt_u32_f32_e32 v2, v2
	s_nop 0
	v_readfirstlane_b32 s44, v2
	s_mul_i32 s43, s43, s44
	s_mul_hi_u32 s43, s44, s43
	s_add_i32 s44, s44, s43
	s_mul_hi_u32 s43, s25, s44
	s_mul_i32 s44, s43, s41
	s_sub_i32 s25, s25, s44
	s_add_i32 s45, s43, 1
	s_sub_i32 s44, s25, s41
	s_cmp_ge_u32 s25, s41
	s_cselect_b32 s43, s45, s43
	s_cselect_b32 s25, s44, s25
	s_add_i32 s44, s43, 1
	s_cmp_ge_u32 s25, s41
	s_cselect_b32 s25, s44, s43
	s_xor_b32 s25, s25, s42
	s_sub_i32 s25, s25, s42
	s_mul_i32 s40, s25, s40
	s_sub_i32 s30, s30, s40
	s_add_i32 s48, s31, s30
	s_cmp_ge_u32 s25, 28
	s_cselect_b32 s30, 4, 0
	s_cselect_b32 s31, 28, 0
	s_sub_i32 s31, s25, s31
	s_lshr_b32 s40, s31, 2
	s_and_b32 s31, s31, 3
	s_add_i32 s30, s30, s31
	s_mul_i32 s31, s30, 3
	s_add_i32 s31, s31, s40
	s_lshl_b32 s30, s30, 2
	s_add_i32 s30, s30, s40
	s_add_i32 s30, s30, 21
	s_cmp_lt_u32 s40, 3
	s_cselect_b32 s25, s31, s30
	s_lshl_b32 s46, s25, 8
